# cvhost pre-barrier stores with a full vmcnt(0) before the hosted consume: the relaxed step-A wait then only leaves the two hosted stores outstanding (no cross-type ordering assumption)
# speedup vs baseline: 1.0086x; 1.0086x over previous
; template <int NB>
; __device__ __forceinline__ void p0_batch(int it0, int stride, int lane, const P0Ptrs& a) {
;     ...
;     for (int q = 0; q < NB; ++q) {
;         const float gs = d[q].gs; const bool hk = d[q].ks != nullptr;
;         const f32x4 t0 = hk ? s0[q] * gs : (f32x4){gs, gs, gs, gs}, t1 = hk ? s1[q] * gs : (f32x4){gs, gs, gs, gs};
; #pragma unroll
;         for (int i = 0; i < 4; ++i) { v[q][i] *= t0[i]; v[q][4 + i] *= t1[i]; }
.LBB0_759:
	s_add_i32 s98, s87, -1
	s_cmp_gt_u32 s98, 19
	s_cbranch_scc1 .Lcv_predone
	s_waitcnt vmcnt(0)
	s_cmp_gt_u32 s32, 6
	s_cbranch_scc1 .Lcv_nomul
	v_mul_f32_e32 v238, v237, v238
	v_mul_f32_e32 v239, v237, v239
	v_mul_f32_e32 v240, v237, v240
	v_mul_f32_e32 v241, v237, v241
	v_mul_f32_e32 v242, v237, v242
	v_mul_f32_e32 v243, v237, v243
	v_mul_f32_e32 v244, v237, v244
	v_mul_f32_e32 v245, v237, v245
